# code placement: one 4-byte pad behind the scan loop so that every later GEMM chain loop sits at its baseline offset modulo 64 bytes (the inserted scan/conversion code had shifted them by 4 mod 8)
# speedup vs baseline: 1.0049x; 1.0049x over previous
.LBB0_1657:
	s_nop 0
	s_branch .LBB0_1623
	s_nop 0
